# v45 + glu GEMM column rounds reversed (2 rounds) so the following up GEMM reads the most recently written residual-stream columns first
# baseline (speedup 1.0000x reference)
;     __device__ bool next(int i, Unit& u) const {
;         const long L = (long)i * G + c; if (L >= nwg) return false;
;         int wgid = (int)L; { const int q = nwg / NXCD, r = nwg % NXCD, xcd = wgid % NXCD, off = wgid / NXCD; wgid = (xcd < r ? xcd * (q + 1) : r * (q + 1) + (xcd - r) * q) + off; }
;         const int nig = WGM * nN, gid = wgid / nig, fm = gid * WGM, gsz = (nM - fm) < WGM ? (nM - fm) : WGM;
;         u.pm = fm + ((wgid % nig) % gsz); u.pn = (wgid % nig) / gsz; return true;
.LBB0_1310:
	s_ashr_i32 s6, s8, 3
	s_add_i32 s6, s10, s6
	s_xor_b32 s6, s6, 0x20
	s_bfe_u32 s100, s6, 0x10006
	s_bfe_u32 s101, s6, 0x40002
	s_andn2_b32 s6, s6, 0x7c
	s_lshl_b32 s100, s100, 2
	s_lshl_b32 s101, s101, 3
	s_or_b32 s6, s6, s100
	s_or_b32 s6, s6, s101
	s_ashr_i32 s7, s6, 31
	s_lshr_b32 s7, s7, 25
	s_add_i32 s7, s6, s7
	s_ashr_i32 s8, s7, 7
	s_and_b32 s7, s7, 0xff80
	s_sub_i32 s6, s6, s7
	s_bfe_i32 s7, s6, 0x80000
	s_bfe_u32 s7, s7, 0x3000c
	s_add_i32 s7, s6, s7
	s_bfe_i32 s9, s7, 0x80000
	s_and_b32 s7, s7, 0xf8
	s_sub_i32 s6, s6, s7
	s_lshl_b32 s8, s8, 3
	s_sext_i32_i16 s9, s9
	s_sext_i32_i8 s6, s6
	s_add_i32 s22, s8, s6
	s_ashr_i32 s6, s9, 3

;     __device__ bool next(int i, Unit& u) const {
;         const long L = (long)i * G + c; if (L >= nwg) return false;
;         int wgid = (int)L; { const int q = nwg / NXCD, r = nwg % NXCD, xcd = wgid % NXCD, off = wgid / NXCD; wgid = (xcd < r ? xcd * (q + 1) : r * (q + 1) + (xcd - r) * q) + off; }
;         const int nig = WGM * nN, gid = wgid / nig, fm = gid * WGM, gsz = (nM - fm) < WGM ? (nM - fm) : WGM;
;         u.pm = fm + ((wgid % nig) % gsz); u.pn = (wgid % nig) / gsz; return true;
; template <class Epi>
; __device__ __forceinline__ void gemm_phase(LAS unsigned char* lds, const Gemm g, const StaticOrder& S, const Epi& E) {
;     ...
;         const bool has_next = S.next(ui + 1, nxt);
.LBB0_1322:
	s_ashr_i32 s3, s3, 3
	s_add_i32 s3, s16, s3
	s_xor_b32 s3, s3, 0x20
	s_bfe_u32 s100, s3, 0x10006
	s_bfe_u32 s101, s3, 0x40002
	s_andn2_b32 s3, s3, 0x7c
	s_lshl_b32 s100, s100, 2
	s_lshl_b32 s101, s101, 3
	s_or_b32 s3, s3, s100
	s_or_b32 s3, s3, s101
	s_ashr_i32 s7, s3, 31
	s_lshr_b32 s7, s7, 25
	s_add_i32 s7, s3, s7
	s_ashr_i32 s12, s7, 7
	s_lshl_b32 s13, s12, 3
	s_sub_i32 s12, 32, s13
	s_min_i32 s16, s12, 8
	s_abs_i32 s12, s16
	v_cvt_f32_u32_e32 v2, s12
	s_sub_i32 s18, 0, s12
	s_and_b32 s7, s7, 0xffffff80
	s_sub_i32 s3, s3, s7
	v_rcp_iflag_f32_e32 v2, v2
	s_abs_i32 s7, s3
	s_xor_b32 s17, s3, s16
	s_ashr_i32 s17, s17, 31
	v_mul_f32_e32 v2, 0x4f7ffffe, v2
	v_cvt_u32_f32_e32 v2, v2
	s_nop 0
	v_readfirstlane_b32 s19, v2
	s_mul_i32 s18, s18, s19
	s_mul_hi_u32 s18, s19, s18
	s_add_i32 s19, s19, s18
	s_mul_hi_u32 s18, s7, s19
	s_mul_i32 s19, s18, s12
	s_sub_i32 s7, s7, s19
	s_add_i32 s20, s18, 1
	s_sub_i32 s19, s7, s12
	s_cmp_ge_u32 s7, s12
	s_cselect_b32 s18, s20, s18
	s_cselect_b32 s7, s19, s7
	s_add_i32 s19, s18, 1
	s_cmp_ge_u32 s7, s12
	s_cselect_b32 s7, s19, s18
	s_xor_b32 s7, s7, s17
	s_sub_i32 s12, s7, s17
	s_mul_i32 s7, s12, s16
	s_sub_i32 s3, s3, s7
	s_add_i32 s16, s13, s3
